# work-queue dequeue: atomic result no longer waited at unit start (returns into nx reg, consumed at unit end), on top of peel+EpiY
# baseline (speedup 1.0000x reference)
.LBB0_265:
	s_and_saveexec_b64 s[0:1], vcc
	s_cbranch_execz .LBB0_269
	s_mov_b64 s[22:23], exec
	v_mbcnt_lo_u32_b32 v0, s22, 0
	v_mbcnt_hi_u32_b32 v0, s23, v0
	v_cmp_eq_u32_e64 s[44:45], 0, v0
	s_and_saveexec_b64 s[14:15], s[44:45]
	s_cbranch_execz .LBB0_268
	s_bcnt1_i32_b64 s3, s[22:23]
	v_mov_b32_e32 v1, s3
	global_atomic_add v121, v5, v1, s[82:83] sc0
.LBB0_268:
	s_or_b64 exec, exec, s[14:15]
.LBB0_269:
	s_or_b64 exec, exec, s[0:1]
	s_ashr_i32 s0, s2, 3
	s_and_b32 s3, s2, 7
	s_ashr_i32 s1, s2, 31
	s_abs_i32 s2, s0
	s_mul_hi_u32 s4, s2, s30
	s_mul_i32 s4, s4, s26
	s_sub_i32 s2, s2, s4
	s_sub_i32 s4, s2, s26
	s_cmp_ge_u32 s2, s26
	s_cselect_b32 s2, s4, s2
	s_sub_i32 s4, s2, s26
	s_cmp_ge_u32 s2, s26
	v_readfirstlane_b32 s22, v189
	s_cselect_b32 s2, s4, s2
	s_xor_b32 s2, s2, s1
	s_ashr_i32 s23, s22, 2
	s_sub_i32 s2, s2, s1
	s_ashr_i32 s1, s0, 31
	s_and_b32 s6, s23, -16
	s_lshl_b32 s7, s3, 7
	s_mul_i32 s5, s0, 0xd0000
	v_readlane_b32 s24, v253, 50
	s_mul_hi_i32 s4, s0, 0xd0000
	v_readlane_b32 s25, v253, 51
	s_add_u32 s5, s24, s5
	s_addc_u32 s8, s25, s4
	s_lshl_b32 s4, s3, 8
	s_add_u32 s4, s5, s4
	s_addc_u32 s5, s8, 0
	v_lshl_add_u64 v[0:1], s[4:5], 0, v[4:5]
	v_lshl_add_u64 v[2:3], v[0:1], 0, v[54:55]
	s_movk_i32 s4, 0x1000
	v_add_co_u32_e64 v6, s[44:45], s4, v2
	v_lshl_add_u64 v[0:1], v[0:1], 0, v[56:57]
	s_nop 0
	v_addc_co_u32_e64 v7, s[44:45], 0, v3, s[44:45]
	global_load_dwordx4 v[38:41], v[2:3], off
	global_load_dwordx4 v[42:45], v[6:7], off
	global_load_dwordx4 v[46:49], v[6:7], off offset:2048
	v_add_co_u32_e64 v6, s[44:45], s4, v0
	global_load_dwordx4 v[50:53], v[0:1], off
	s_nop 0
	v_addc_co_u32_e64 v7, s[44:45], 0, v1, s[44:45]
	global_load_dwordx4 v[94:97], v[2:3], off offset:2048
	global_load_dwordx4 v[124:127], v[6:7], off
	global_load_dwordx4 v[128:131], v[6:7], off offset:2048
	v_or_b32_e32 v122, s6, v58
	v_lshlrev_b32_e32 v2, 7, v122
	s_cmp_eq_u32 s2, 0
	v_ashrrev_i32_e32 v3, 31, v2
	global_load_dwordx4 v[132:135], v[0:1], off offset:2048
	s_cselect_b64 s[14:15], -1, 0
	v_lshl_add_u64 v[2:3], v[2:3], 1, v[60:61]
	s_lshl_b64 s[4:5], s[0:1], 19
	s_lshl_b32 s96, s3, 16
	v_lshl_add_u64 v[2:3], v[2:3], 0, s[4:5]
	v_lshl_add_u64 v[0:1], v[2:3], 0, s[96:97]
	s_mov_b32 s3, 0x8000
	global_load_dwordx4 v[34:37], v[0:1], off
	global_load_dwordx4 v[30:33], v[0:1], off offset:64
	global_load_dwordx4 v[26:29], v[0:1], off offset:128
	global_load_dwordx4 v[22:25], v[0:1], off offset:192
	v_add_co_u32_e64 v0, s[44:45], s3, v0
	s_add_i32 s6, s6, s7
	s_nop 0
	v_addc_co_u32_e64 v1, s[44:45], 0, v1, s[44:45]
	s_lshl_b64 s[0:1], s[0:1], 6
	global_load_dwordx4 v[18:21], v[0:1], off
	global_load_dwordx4 v[14:17], v[0:1], off offset:64
	global_load_dwordx4 v[10:13], v[0:1], off offset:128
	global_load_dwordx4 v[6:9], v[0:1], off offset:192
	v_or_b32_e32 v92, s6, v59
	v_or_b32_e32 v88, s0, v58
	v_mov_b64_e32 v[0:1], s[24:25]
	s_movk_i32 s6, 0x3400
	v_ashrrev_i32_e32 v93, 31, v92
	v_mad_u64_u32 v[2:3], s[4:5], v88, s6, v[0:1]
	v_mad_i32_i24 v3, s1, v185, v3
	v_lshlrev_b64 v[78:79], 1, v[92:93]
	v_or_b32_e32 v84, s0, v62
	v_lshl_add_u64 v[2:3], v[2:3], 0, v[78:79]
	s_movk_i32 s3, 0x2000
	v_mad_u64_u32 v[76:77], s[4:5], v84, s6, v[0:1]
	v_add_co_u32_e64 v2, s[44:45], s3, v2
	v_mad_i32_i24 v77, s1, v185, v77
	s_nop 0
	v_addc_co_u32_e64 v3, s[44:45], 0, v3, s[44:45]
	v_lshl_add_u64 v[76:77], v[76:77], 0, v[78:79]
	v_add_co_u32_e64 v82, s[44:45], s3, v76
	v_or_b32_e32 v80, s0, v64
	s_nop 0
	v_addc_co_u32_e64 v83, s[44:45], 0, v77, s[44:45]
	v_mad_u64_u32 v[76:77], s[4:5], v80, s6, v[0:1]
	v_mad_i32_i24 v77, s1, v185, v77
	v_lshl_add_u64 v[76:77], v[76:77], 0, v[78:79]
	v_add_co_u32_e64 v136, s[44:45], s3, v76
	v_or_b32_e32 v76, s0, v66
	v_mad_u64_u32 v[0:1], s[4:5], v76, s6, v[0:1]
	v_mad_i32_i24 v1, s1, v185, v1
	v_addc_co_u32_e64 v137, s[44:45], 0, v77, s[44:45]
	v_lshl_add_u64 v[0:1], v[0:1], 0, v[78:79]
	v_add_co_u32_e64 v0, s[44:45], s3, v0
	v_mov_b32_e32 v89, s1
	s_nop 0
	v_addc_co_u32_e64 v1, s[44:45], 0, v1, s[44:45]
	v_readlane_b32 s44, v254, 24
	global_load_dwordx2 v[90:91], v[2:3], off
	global_load_dwordx2 v[86:87], v[82:83], off
	s_nop 0
	global_load_dwordx2 v[82:83], v[136:137], off
	global_load_dwordx2 v[78:79], v[0:1], off
	v_readlane_b32 s54, v254, 34
	v_readlane_b32 s55, v254, 35
	v_readlane_b32 s45, v254, 25
	v_mov_b32_e32 v85, s1
	v_lshl_add_u64 v[0:1], v[92:93], 2, s[54:55]
	global_load_dwordx4 v[0:3], v[0:1], off
	s_waitcnt vmcnt(0)
	ds_write_b128 v68, v[38:41] offset:4096
	ds_write_b128 v68, v[38:41] offset:21504
	ds_write_b128 v68, v[42:45] offset:38912
	ds_write_b128 v68, v[46:49] offset:56320
	ds_write_b16 v65, v94
	ds_write_b16_d16_hi v65, v94 offset:144
	ds_write_b16 v65, v95 offset:288
	ds_write_b16_d16_hi v65, v95 offset:432
	ds_write_b16 v65, v96 offset:576
	ds_write_b16_d16_hi v65, v96 offset:720
	ds_write_b16 v65, v97 offset:864
	ds_write_b16_d16_hi v65, v97 offset:1008
	ds_write_b128 v70, v[50:53] offset:4096
	ds_write_b128 v70, v[50:53] offset:21504
	ds_write_b128 v70, v[124:127] offset:38912
	ds_write_b128 v70, v[128:131] offset:56320
	ds_write_b16 v67, v132
	ds_write_b16_d16_hi v67, v132 offset:144
	ds_write_b16 v67, v133 offset:288
	ds_write_b16_d16_hi v67, v133 offset:432
	ds_write_b16 v67, v134 offset:576
	ds_write_b16_d16_hi v67, v134 offset:720
	ds_write_b16 v67, v135 offset:864
	ds_write_b16_d16_hi v67, v135 offset:1008
	s_waitcnt lgkmcnt(0)
	s_barrier
	ds_read_u16 v38, v71 offset:38912
	ds_read_u16 v39, v71 offset:39184
	ds_read_u16 v40, v71 offset:39456
	ds_read_u16 v41, v71 offset:39728
	ds_read_u16 v42, v71 offset:40000
	ds_read_u16 v43, v71 offset:40272
	ds_read_u16 v44, v71 offset:40544
	ds_read_u16 v45, v71 offset:40816
	s_waitcnt lgkmcnt(7)
	v_lshlrev_b32_e32 v38, 16, v38
	v_cndmask_b32_e64 v127, v38, 0, s[14:15]
	s_waitcnt lgkmcnt(6)
	v_lshlrev_b32_e32 v39, 16, v39
	v_add_f32_e32 v38, 0, v127
	v_cndmask_b32_e64 v39, v39, 0, s[14:15]
	s_waitcnt lgkmcnt(5)
	v_lshlrev_b32_e32 v40, 16, v40
	v_add_f32_e32 v38, v38, v39
	v_cndmask_b32_e64 v40, v40, 0, s[14:15]
	s_waitcnt lgkmcnt(4)
	v_lshlrev_b32_e32 v41, 16, v41
	v_add_f32_e32 v38, v38, v40
	v_cndmask_b32_e64 v41, v41, 0, s[14:15]
	s_waitcnt lgkmcnt(3)
	v_lshlrev_b32_e32 v42, 16, v42
	v_add_f32_e32 v38, v38, v41
	v_cndmask_b32_e64 v42, v42, 0, s[14:15]
	s_waitcnt lgkmcnt(2)
	v_lshlrev_b32_e32 v43, 16, v43
	v_add_f32_e32 v38, v38, v42
	v_cndmask_b32_e64 v43, v43, 0, s[14:15]
	s_waitcnt lgkmcnt(1)
	v_lshlrev_b32_e32 v44, 16, v44
	v_add_f32_e32 v38, v38, v43
	v_cndmask_b32_e64 v44, v44, 0, s[14:15]
	s_waitcnt lgkmcnt(0)
	v_lshlrev_b32_e32 v45, 16, v45
	ds_read_u16 v46, v71 offset:41088
	ds_read_u16 v47, v71 offset:41360
	ds_read_u16 v48, v71 offset:41632
	ds_read_u16 v49, v71 offset:41904
	ds_read_u16 v50, v71 offset:42176
	ds_read_u16 v51, v71 offset:42448
	ds_read_u16 v52, v71 offset:42720
	ds_read_u16 v53, v71 offset:42992
	v_add_f32_e32 v38, v38, v44
	v_cndmask_b32_e64 v45, v45, 0, s[14:15]
	s_waitcnt lgkmcnt(7)
	v_lshlrev_b32_e32 v46, 16, v46
	v_add_f32_e32 v38, v38, v45
	v_cndmask_b32_e64 v46, v46, 0, s[14:15]
	s_waitcnt lgkmcnt(6)
	v_lshlrev_b32_e32 v47, 16, v47
	v_add_f32_e32 v38, v38, v46
	v_cndmask_b32_e64 v47, v47, 0, s[14:15]
	s_waitcnt lgkmcnt(5)
	v_lshlrev_b32_e32 v48, 16, v48
	v_add_f32_e32 v38, v38, v47
	v_cndmask_b32_e64 v48, v48, 0, s[14:15]
	s_waitcnt lgkmcnt(4)
	v_lshlrev_b32_e32 v49, 16, v49
	v_add_f32_e32 v38, v38, v48
	v_cndmask_b32_e64 v49, v49, 0, s[14:15]
	s_waitcnt lgkmcnt(3)
	v_lshlrev_b32_e32 v50, 16, v50
	v_add_f32_e32 v38, v38, v49
	v_cndmask_b32_e64 v50, v50, 0, s[14:15]
	s_waitcnt lgkmcnt(2)
	v_lshlrev_b32_e32 v51, 16, v51
	v_add_f32_e32 v38, v38, v50
	v_cndmask_b32_e64 v51, v51, 0, s[14:15]
	s_waitcnt lgkmcnt(1)
	v_lshlrev_b32_e32 v52, 16, v52
	v_add_f32_e32 v38, v38, v51
	v_cndmask_b32_e64 v52, v52, 0, s[14:15]
	s_waitcnt lgkmcnt(0)
	v_lshlrev_b32_e32 v53, 16, v53
	ds_read_u16 v77, v71 offset:43264
	ds_read_u16 v94, v71 offset:43536
	ds_read_u16 v95, v71 offset:43808
	ds_read_u16 v96, v71 offset:44080
	ds_read_u16 v97, v71 offset:44352
	ds_read_u16 v123, v71 offset:44624
	ds_read_u16 v124, v71 offset:44896
	ds_read_u16 v125, v71 offset:45168
	v_or_b32_e32 v126, s2, v69
	v_add_f32_e32 v38, v38, v52
	v_cndmask_b32_e64 v53, v53, 0, s[14:15]
	s_waitcnt lgkmcnt(7)
	v_lshlrev_b32_e32 v77, 16, v77
	v_cmp_eq_u32_e64 s[44:45], 0, v126
	v_add_f32_e32 v38, v38, v53
	s_waitcnt lgkmcnt(6)
	v_lshlrev_b32_e32 v94, 16, v94
	v_cndmask_b32_e64 v77, v77, 0, s[44:45]
	v_add_f32_e32 v38, v38, v77
	v_cndmask_b32_e64 v94, v94, 0, s[44:45]
	s_waitcnt lgkmcnt(5)
	v_lshlrev_b32_e32 v95, 16, v95
	v_add_f32_e32 v38, v38, v94
	v_cndmask_b32_e64 v95, v95, 0, s[44:45]
	s_waitcnt lgkmcnt(4)
	v_lshlrev_b32_e32 v96, 16, v96
	v_add_f32_e32 v38, v38, v95
	v_cndmask_b32_e64 v96, v96, 0, s[44:45]
	s_waitcnt lgkmcnt(3)
	v_lshlrev_b32_e32 v97, 16, v97
	v_add_f32_e32 v38, v38, v96
	v_cndmask_b32_e64 v97, v97, 0, s[44:45]
	s_waitcnt lgkmcnt(2)
	v_lshlrev_b32_e32 v123, 16, v123
	v_add_f32_e32 v38, v38, v97
	v_cndmask_b32_e64 v123, v123, 0, s[44:45]
	s_waitcnt lgkmcnt(1)
	v_lshlrev_b32_e32 v124, 16, v124
	v_add_f32_e32 v38, v38, v123
	v_cndmask_b32_e64 v124, v124, 0, s[44:45]
	s_waitcnt lgkmcnt(0)
	v_lshlrev_b32_e32 v125, 16, v125
	ds_read_u16 v126, v71 offset:45440
	ds_read_u16 v128, v71 offset:45712
	ds_read_u16 v129, v71 offset:45984
	ds_read_u16 v130, v71 offset:46256
	ds_read_u16 v131, v71 offset:46528
	ds_read_u16 v132, v71 offset:46800
	ds_read_u16 v133, v71 offset:47072
	ds_read_u16 v134, v71 offset:47344
	v_add_f32_e32 v38, v38, v124
	v_cndmask_b32_e64 v125, v125, 0, s[44:45]
	s_waitcnt lgkmcnt(7)
	v_lshlrev_b32_e32 v126, 16, v126
	v_add_f32_e32 v38, v38, v125
	v_cndmask_b32_e64 v126, v126, 0, s[44:45]
	s_waitcnt lgkmcnt(6)
	v_lshlrev_b32_e32 v128, 16, v128
	v_add_f32_e32 v38, v38, v126
	v_cndmask_b32_e64 v128, v128, 0, s[44:45]
	s_waitcnt lgkmcnt(5)
	v_lshlrev_b32_e32 v129, 16, v129
	v_add_f32_e32 v38, v38, v128
	v_cndmask_b32_e64 v129, v129, 0, s[44:45]
	s_waitcnt lgkmcnt(4)
	v_lshlrev_b32_e32 v130, 16, v130
	v_add_f32_e32 v38, v38, v129
	v_cndmask_b32_e64 v130, v130, 0, s[44:45]
	s_waitcnt lgkmcnt(3)
	v_lshlrev_b32_e32 v131, 16, v131
	v_add_f32_e32 v38, v38, v130
	v_cndmask_b32_e64 v131, v131, 0, s[44:45]
	s_waitcnt lgkmcnt(2)
	v_lshlrev_b32_e32 v132, 16, v132
	v_add_f32_e32 v38, v38, v131
	v_cndmask_b32_e64 v132, v132, 0, s[44:45]
	s_waitcnt lgkmcnt(1)
	v_lshlrev_b32_e32 v133, 16, v133
	v_add_f32_e32 v38, v38, v132
	v_cndmask_b32_e64 v133, v133, 0, s[44:45]
	s_waitcnt lgkmcnt(0)
	v_lshlrev_b32_e32 v134, 16, v134
	v_add_f32_e32 v38, v38, v133
	v_cndmask_b32_e64 v134, v134, 0, s[44:45]
	v_add_f32_e32 v38, v38, v134
	ds_write_b32 v73, v38
	s_waitcnt lgkmcnt(0)
	s_barrier
	ds_read_b32 v135, v75
	v_mul_f32_e32 v38, 0x3fb8aa3b, v134
	v_mul_f32_e32 v133, 0x3fb8aa3b, v133
	v_mul_f32_e32 v132, 0x3fb8aa3b, v132
	v_mul_f32_e32 v131, 0x3fb8aa3b, v131
	v_mul_f32_e32 v130, 0x3fb8aa3b, v130
	v_mul_f32_e32 v129, 0x3fb8aa3b, v129
	v_mul_f32_e32 v128, 0x3fb8aa3b, v128
	v_mul_f32_e32 v126, 0x3fb8aa3b, v126
	v_mul_f32_e32 v125, 0x3fb8aa3b, v125
	v_mul_f32_e32 v124, 0x3fb8aa3b, v124
	v_mul_f32_e32 v123, 0x3fb8aa3b, v123
	v_mul_f32_e32 v134, 0x3fb8aa3b, v97
	v_mul_f32_e32 v136, 0x3fb8aa3b, v96
	v_mul_f32_e32 v95, 0x3fb8aa3b, v95
	v_mul_f32_e32 v137, 0x3fb8aa3b, v94
	v_mul_f32_e32 v77, 0x3fb8aa3b, v77
	v_mul_f32_e32 v53, 0x3fb8aa3b, v53
	v_mul_f32_e32 v138, 0x3fb8aa3b, v52
	v_mul_f32_e32 v51, 0x3fb8aa3b, v51
	v_mul_f32_e32 v50, 0x3fb8aa3b, v50
	v_mul_f32_e32 v139, 0x3fb8aa3b, v49
	v_mul_f32_e32 v140, 0x3fb8aa3b, v48
	v_mul_f32_e32 v141, 0x3fb8aa3b, v47
	v_mul_f32_e32 v142, 0x3fb8aa3b, v46
	v_mul_f32_e32 v143, 0x3fb8aa3b, v45
	v_mul_f32_e32 v144, 0x3fb8aa3b, v44
	v_mul_f32_e32 v145, 0x3fb8aa3b, v43
	v_mul_f32_e32 v146, 0x3fb8aa3b, v42
	v_mul_f32_e32 v147, 0x3fb8aa3b, v41
	v_mul_f32_e32 v148, 0x3fb8aa3b, v40
	v_mul_f32_e32 v149, 0x3fb8aa3b, v39
	v_exp_f32_e32 v47, v38
	v_exp_f32_e32 v49, v133
	v_exp_f32_e32 v46, v132
	v_exp_f32_e32 v44, v131
	v_exp_f32_e32 v41, v130
	v_exp_f32_e32 v40, v129
	v_exp_f32_e32 v39, v128
	v_exp_f32_e32 v38, v126
	v_exp_f32_e32 v97, v125
	v_exp_f32_e32 v96, v124
	v_exp_f32_e32 v94, v123
	v_exp_f32_e32 v52, v134
	v_exp_f32_e32 v48, v136
	v_exp_f32_e32 v45, v95
	v_exp_f32_e32 v43, v137
	v_exp_f32_e32 v42, v77
	v_exp_f32_e32 v130, v53
	v_exp_f32_e32 v129, v138
	v_exp_f32_e32 v126, v51
	v_exp_f32_e32 v123, v50
	v_exp_f32_e32 v95, v139
	v_exp_f32_e32 v53, v140
	v_exp_f32_e32 v51, v141
	v_exp_f32_e32 v50, v142
	v_exp_f32_e32 v134, v143
	v_exp_f32_e32 v133, v144
	v_exp_f32_e32 v132, v145
	v_exp_f32_e32 v131, v146
	v_exp_f32_e32 v128, v147
	v_exp_f32_e32 v125, v148
	v_exp_f32_e32 v124, v149
	v_mov_b32_e32 v81, s1
	v_mov_b32_e32 v77, s1
	s_waitcnt lgkmcnt(0)
	v_mul_f32_e32 v135, 0x3fb8aa3b, v135
	v_mul_f32_e32 v127, 0x3fb8aa3b, v127
	v_readlane_b32 s46, v254, 26
	v_readlane_b32 s47, v254, 27
	v_readlane_b32 s48, v254, 28
	v_readlane_b32 s49, v254, 29
	v_readlane_b32 s50, v254, 30
	v_readlane_b32 s51, v254, 31
	v_readlane_b32 s52, v254, 32
	v_readlane_b32 s53, v254, 33
	v_readlane_b32 s56, v254, 36
	v_readlane_b32 s57, v254, 37
	v_readlane_b32 s58, v254, 38
	v_readlane_b32 s59, v254, 39
	s_and_saveexec_b64 s[0:1], s[38:39]
	s_xor_b64 s[44:45], exec, s[0:1]
	s_cbranch_execz .LBB0_271
	v_cndmask_b32_e64 v135, 0, v135, s[40:41]
	v_exp_f32_e32 v135, v135
	v_sub_f32_e32 v137, 1.0, v47
	v_mul_f32_e32 v136, v47, v135
	ds_read_u16 v135, v71 offset:12528
	v_rcp_f32_e32 v139, v136
	s_waitcnt lgkmcnt(0)
	v_lshlrev_b32_e32 v138, 16, v135
	v_pk_mul_f32 v[138:139], v[136:137], v[138:139]
	v_mul_f32_e32 v136, v49, v136
	v_cvt_pk_bf16_f32 v47, v138, v139
	ds_write_b16 v71, v47 offset:12528
	ds_write_b16_d16_hi v71, v47 offset:47344
	ds_read_u16 v47, v71 offset:12256
	v_rcp_f32_e32 v139, v136
	v_sub_f32_e32 v137, 1.0, v49
	s_waitcnt lgkmcnt(0)
	v_lshlrev_b32_e32 v138, 16, v47
	v_pk_mul_f32 v[138:139], v[136:137], v[138:139]
	v_mul_f32_e32 v136, v46, v136
	v_cvt_pk_bf16_f32 v47, v138, v139
	ds_write_b16 v71, v47 offset:12256
	ds_write_b16_d16_hi v71, v47 offset:47072
	ds_read_u16 v47, v71 offset:11984
	v_rcp_f32_e32 v139, v136
	v_sub_f32_e32 v137, 1.0, v46
	s_waitcnt lgkmcnt(0)
	v_lshlrev_b32_e32 v138, 16, v47
	v_pk_mul_f32 v[46:47], v[136:137], v[138:139]
	s_nop 0
	v_cvt_pk_bf16_f32 v46, v46, v47
	ds_write_b16 v71, v46 offset:11984
	ds_write_b16_d16_hi v71, v46 offset:46800
	ds_read_u16 v47, v71 offset:11712
	v_mul_f32_e32 v46, v44, v136
	v_rcp_f32_e32 v137, v46
	s_waitcnt lgkmcnt(0)
	v_lshlrev_b32_e32 v136, 16, v47
	v_sub_f32_e32 v47, 1.0, v44
	v_pk_mul_f32 v[136:137], v[46:47], v[136:137]
	v_mul_f32_e32 v46, v41, v46
	v_cvt_pk_bf16_f32 v44, v136, v137
	ds_write_b16 v71, v44 offset:11712
	ds_write_b16_d16_hi v71, v44 offset:46528
	ds_read_u16 v44, v71 offset:11440
	v_rcp_f32_e32 v137, v46
	v_sub_f32_e32 v47, 1.0, v41
	s_waitcnt lgkmcnt(0)
	v_lshlrev_b32_e32 v136, 16, v44
	v_pk_mul_f32 v[136:137], v[46:47], v[136:137]
	v_mul_f32_e32 v46, v40, v46
	v_cvt_pk_bf16_f32 v41, v136, v137
	ds_write_b16 v71, v41 offset:11440
	ds_write_b16_d16_hi v71, v41 offset:46256
	ds_read_u16 v41, v71 offset:11168
	v_rcp_f32_e32 v137, v46
	v_sub_f32_e32 v47, 1.0, v40
	s_waitcnt lgkmcnt(0)
	v_lshlrev_b32_e32 v136, 16, v41
	v_pk_mul_f32 v[40:41], v[46:47], v[136:137]
	s_nop 0
	v_cvt_pk_bf16_f32 v40, v40, v41
	ds_write_b16 v71, v40 offset:11168
	ds_write_b16_d16_hi v71, v40 offset:45984
	ds_read_u16 v41, v71 offset:10896
	v_mul_f32_e32 v40, v39, v46
	v_rcp_f32_e32 v47, v40
	s_waitcnt lgkmcnt(0)
	v_lshlrev_b32_e32 v46, 16, v41
	v_sub_f32_e32 v41, 1.0, v39
	v_pk_mul_f32 v[46:47], v[40:41], v[46:47]
	v_mul_f32_e32 v40, v38, v40
	v_cvt_pk_bf16_f32 v39, v46, v47
	ds_write_b16 v71, v39 offset:10896
	ds_write_b16_d16_hi v71, v39 offset:45712
	ds_read_u16 v39, v71 offset:10624
	v_rcp_f32_e32 v47, v40
	v_sub_f32_e32 v41, 1.0, v38
	s_waitcnt lgkmcnt(0)
	v_lshlrev_b32_e32 v46, 16, v39
	v_pk_mul_f32 v[38:39], v[40:41], v[46:47]
	s_nop 0
	v_cvt_pk_bf16_f32 v38, v38, v39
	ds_write_b16 v71, v38 offset:10624
	ds_write_b16_d16_hi v71, v38 offset:45440
	ds_read_u16 v39, v71 offset:10352
	v_mul_f32_e32 v38, v97, v40
	v_rcp_f32_e32 v41, v38
	s_waitcnt lgkmcnt(0)
	v_lshlrev_b32_e32 v40, 16, v39
	v_sub_f32_e32 v39, 1.0, v97
	v_pk_mul_f32 v[40:41], v[38:39], v[40:41]
	v_mul_f32_e32 v38, v96, v38
	v_cvt_pk_bf16_f32 v39, v40, v41
	ds_write_b16 v71, v39 offset:10352
	ds_write_b16_d16_hi v71, v39 offset:45168
	ds_read_u16 v39, v71 offset:10080
	v_rcp_f32_e32 v41, v38
	s_waitcnt lgkmcnt(0)
	v_lshlrev_b32_e32 v40, 16, v39
	v_sub_f32_e32 v39, 1.0, v96
	v_pk_mul_f32 v[40:41], v[38:39], v[40:41]
	v_mul_f32_e32 v38, v94, v38
	v_cvt_pk_bf16_f32 v39, v40, v41
	ds_write_b16 v71, v39 offset:10080
	ds_write_b16_d16_hi v71, v39 offset:44896
	ds_read_u16 v39, v71 offset:9808
	v_rcp_f32_e32 v41, v38
	s_waitcnt lgkmcnt(0)
	v_lshlrev_b32_e32 v40, 16, v39
	v_sub_f32_e32 v39, 1.0, v94
	v_pk_mul_f32 v[40:41], v[38:39], v[40:41]
	v_mul_f32_e32 v38, v52, v38
	v_cvt_pk_bf16_f32 v39, v40, v41
	ds_write_b16 v71, v39 offset:9808
	ds_write_b16_d16_hi v71, v39 offset:44624
	ds_read_u16 v39, v71 offset:9536
	v_rcp_f32_e32 v41, v38
	s_waitcnt lgkmcnt(0)
	v_lshlrev_b32_e32 v40, 16, v39
	v_sub_f32_e32 v39, 1.0, v52
	v_pk_mul_f32 v[40:41], v[38:39], v[40:41]
	v_mul_f32_e32 v38, v48, v38
	v_cvt_pk_bf16_f32 v39, v40, v41
	ds_write_b16 v71, v39 offset:9536
	ds_write_b16_d16_hi v71, v39 offset:44352
	ds_read_u16 v39, v71 offset:9264
	v_rcp_f32_e32 v41, v38
	s_waitcnt lgkmcnt(0)
	v_lshlrev_b32_e32 v40, 16, v39
	v_sub_f32_e32 v39, 1.0, v48
	v_pk_mul_f32 v[40:41], v[38:39], v[40:41]
	v_mul_f32_e32 v38, v45, v38
	v_cvt_pk_bf16_f32 v39, v40, v41
	ds_write_b16 v71, v39 offset:9264
	ds_write_b16_d16_hi v71, v39 offset:44080
	ds_read_u16 v39, v71 offset:8992
	v_rcp_f32_e32 v41, v38
	s_waitcnt lgkmcnt(0)
	v_lshlrev_b32_e32 v40, 16, v39
	v_sub_f32_e32 v39, 1.0, v45
	v_pk_mul_f32 v[40:41], v[38:39], v[40:41]
	v_mul_f32_e32 v38, v43, v38
	v_cvt_pk_bf16_f32 v39, v40, v41
	ds_write_b16 v71, v39 offset:8992
	ds_write_b16_d16_hi v71, v39 offset:43808
	ds_read_u16 v39, v71 offset:8720
	v_rcp_f32_e32 v41, v38
	s_waitcnt lgkmcnt(0)
	v_lshlrev_b32_e32 v40, 16, v39
	v_sub_f32_e32 v39, 1.0, v43
	v_pk_mul_f32 v[40:41], v[38:39], v[40:41]
	v_mul_f32_e32 v38, v42, v38
	v_cvt_pk_bf16_f32 v39, v40, v41
	ds_write_b16 v71, v39 offset:8720
	ds_write_b16_d16_hi v71, v39 offset:43536
	ds_read_u16 v39, v71 offset:8448
	v_rcp_f32_e32 v41, v38
	s_waitcnt lgkmcnt(0)
	v_lshlrev_b32_e32 v40, 16, v39
	v_sub_f32_e32 v39, 1.0, v42
	v_pk_mul_f32 v[40:41], v[38:39], v[40:41]
	v_mul_f32_e32 v38, v130, v38
	v_cvt_pk_bf16_f32 v39, v40, v41
	ds_write_b16 v71, v39 offset:8448
	ds_write_b16_d16_hi v71, v39 offset:43264
	ds_read_u16 v39, v71 offset:8176
	v_rcp_f32_e32 v41, v38
	s_waitcnt lgkmcnt(0)
	v_lshlrev_b32_e32 v40, 16, v39
	v_sub_f32_e32 v39, 1.0, v130
	v_pk_mul_f32 v[40:41], v[38:39], v[40:41]
	v_mul_f32_e32 v38, v129, v38
	v_cvt_pk_bf16_f32 v39, v40, v41
	ds_write_b16 v71, v39 offset:8176
	ds_write_b16_d16_hi v71, v39 offset:42992
	ds_read_u16 v39, v71 offset:7904
	v_rcp_f32_e32 v41, v38
	s_waitcnt lgkmcnt(0)
	v_lshlrev_b32_e32 v40, 16, v39
	v_sub_f32_e32 v39, 1.0, v129
	v_pk_mul_f32 v[40:41], v[38:39], v[40:41]
	v_mul_f32_e32 v38, v126, v38
	v_cvt_pk_bf16_f32 v39, v40, v41
	ds_write_b16 v71, v39 offset:7904
	ds_write_b16_d16_hi v71, v39 offset:42720
	ds_read_u16 v39, v71 offset:7632
	v_rcp_f32_e32 v41, v38
	s_waitcnt lgkmcnt(0)
	v_lshlrev_b32_e32 v40, 16, v39
	v_sub_f32_e32 v39, 1.0, v126
	v_pk_mul_f32 v[40:41], v[38:39], v[40:41]
	v_mul_f32_e32 v38, v123, v38
	v_cvt_pk_bf16_f32 v39, v40, v41
	ds_write_b16 v71, v39 offset:7632
	ds_write_b16_d16_hi v71, v39 offset:42448
	ds_read_u16 v39, v71 offset:7360
	v_rcp_f32_e32 v41, v38
	s_waitcnt lgkmcnt(0)
	v_lshlrev_b32_e32 v40, 16, v39
	v_sub_f32_e32 v39, 1.0, v123
	v_pk_mul_f32 v[40:41], v[38:39], v[40:41]
	v_mul_f32_e32 v38, v95, v38
	v_cvt_pk_bf16_f32 v39, v40, v41
	ds_write_b16 v71, v39 offset:7360
	ds_write_b16_d16_hi v71, v39 offset:42176
	ds_read_u16 v39, v71 offset:7088
	v_rcp_f32_e32 v41, v38
	s_waitcnt lgkmcnt(0)
	v_lshlrev_b32_e32 v40, 16, v39
	v_sub_f32_e32 v39, 1.0, v95
	v_pk_mul_f32 v[40:41], v[38:39], v[40:41]
	v_mul_f32_e32 v38, v53, v38
	v_cvt_pk_bf16_f32 v39, v40, v41
	ds_write_b16 v71, v39 offset:7088
	ds_write_b16_d16_hi v71, v39 offset:41904
	ds_read_u16 v39, v71 offset:6816
	v_rcp_f32_e32 v41, v38
	s_waitcnt lgkmcnt(0)
	v_lshlrev_b32_e32 v40, 16, v39
	v_sub_f32_e32 v39, 1.0, v53
	v_pk_mul_f32 v[40:41], v[38:39], v[40:41]
	v_mul_f32_e32 v38, v51, v38
	v_cvt_pk_bf16_f32 v39, v40, v41
	ds_write_b16 v71, v39 offset:6816
	ds_write_b16_d16_hi v71, v39 offset:41632
	ds_read_u16 v39, v71 offset:6544
	v_rcp_f32_e32 v41, v38
	s_waitcnt lgkmcnt(0)
	v_lshlrev_b32_e32 v40, 16, v39
	v_sub_f32_e32 v39, 1.0, v51
	v_pk_mul_f32 v[40:41], v[38:39], v[40:41]
	v_mul_f32_e32 v38, v50, v38
	v_cvt_pk_bf16_f32 v39, v40, v41
	ds_write_b16 v71, v39 offset:6544
	ds_write_b16_d16_hi v71, v39 offset:41360
	ds_read_u16 v39, v71 offset:6272
	v_rcp_f32_e32 v41, v38
	s_waitcnt lgkmcnt(0)
	v_lshlrev_b32_e32 v40, 16, v39
	v_sub_f32_e32 v39, 1.0, v50
	v_pk_mul_f32 v[40:41], v[38:39], v[40:41]
	v_mul_f32_e32 v38, v134, v38
	v_cvt_pk_bf16_f32 v39, v40, v41
	ds_write_b16 v71, v39 offset:6272
	ds_write_b16_d16_hi v71, v39 offset:41088
	ds_read_u16 v39, v71 offset:6000
	v_rcp_f32_e32 v41, v38
	s_waitcnt lgkmcnt(0)
	v_lshlrev_b32_e32 v40, 16, v39
	v_sub_f32_e32 v39, 1.0, v134
	v_pk_mul_f32 v[40:41], v[38:39], v[40:41]
	v_mul_f32_e32 v38, v133, v38
	v_cvt_pk_bf16_f32 v39, v40, v41
	ds_write_b16 v71, v39 offset:6000
	ds_write_b16_d16_hi v71, v39 offset:40816
	ds_read_u16 v39, v71 offset:5728
	v_rcp_f32_e32 v41, v38
	s_waitcnt lgkmcnt(0)
	v_lshlrev_b32_e32 v40, 16, v39
	v_sub_f32_e32 v39, 1.0, v133
	v_pk_mul_f32 v[40:41], v[38:39], v[40:41]
	v_mul_f32_e32 v38, v132, v38
	v_cvt_pk_bf16_f32 v39, v40, v41
	ds_write_b16 v71, v39 offset:5728
	ds_write_b16_d16_hi v71, v39 offset:40544
	ds_read_u16 v39, v71 offset:5456
	v_rcp_f32_e32 v41, v38
	s_waitcnt lgkmcnt(0)
	v_lshlrev_b32_e32 v40, 16, v39
	v_sub_f32_e32 v39, 1.0, v132
	v_pk_mul_f32 v[40:41], v[38:39], v[40:41]
	v_mul_f32_e32 v38, v131, v38
	v_cvt_pk_bf16_f32 v39, v40, v41
	ds_write_b16 v71, v39 offset:5456
	ds_write_b16_d16_hi v71, v39 offset:40272
	ds_read_u16 v39, v71 offset:5184
	v_rcp_f32_e32 v41, v38
	s_waitcnt lgkmcnt(0)
	v_lshlrev_b32_e32 v40, 16, v39
	v_sub_f32_e32 v39, 1.0, v131
	v_pk_mul_f32 v[40:41], v[38:39], v[40:41]
	v_mul_f32_e32 v38, v128, v38
	v_cvt_pk_bf16_f32 v39, v40, v41
	ds_write_b16 v71, v39 offset:5184
	ds_write_b16_d16_hi v71, v39 offset:40000
	ds_read_u16 v39, v71 offset:4912
	v_rcp_f32_e32 v41, v38
	s_waitcnt lgkmcnt(0)
	v_lshlrev_b32_e32 v40, 16, v39
	v_sub_f32_e32 v39, 1.0, v128
	v_pk_mul_f32 v[40:41], v[38:39], v[40:41]
	v_mul_f32_e32 v38, v125, v38
	v_cvt_pk_bf16_f32 v39, v40, v41
	ds_write_b16 v71, v39 offset:4912
	ds_write_b16_d16_hi v71, v39 offset:39728
	ds_read_u16 v39, v71 offset:4640
	v_rcp_f32_e32 v41, v38
	s_waitcnt lgkmcnt(0)
	v_lshlrev_b32_e32 v40, 16, v39
	v_sub_f32_e32 v39, 1.0, v125
	v_pk_mul_f32 v[40:41], v[38:39], v[40:41]
	v_mul_f32_e32 v38, v124, v38
	v_cvt_pk_bf16_f32 v39, v40, v41
	ds_write_b16 v71, v39 offset:4640
	ds_write_b16_d16_hi v71, v39 offset:39456
	ds_read_u16 v39, v71 offset:4368
	v_rcp_f32_e32 v41, v38
	s_waitcnt lgkmcnt(0)
	v_lshlrev_b32_e32 v40, 16, v39
	v_sub_f32_e32 v39, 1.0, v124
	v_pk_mul_f32 v[40:41], v[38:39], v[40:41]
	s_nop 0
	v_cvt_pk_bf16_f32 v39, v40, v41
	ds_write_b16 v71, v39 offset:4368
	ds_write_b16_d16_hi v71, v39 offset:39184
	v_exp_f32_e32 v39, v127
	ds_read_u16 v40, v71 offset:4096
	v_mul_f32_e32 v38, v39, v38
	v_rcp_f32_e32 v41, v38
	s_waitcnt lgkmcnt(0)
	v_lshlrev_b32_e32 v40, 16, v40
	v_sub_f32_e32 v39, 1.0, v39
	v_pk_mul_f32 v[38:39], v[38:39], v[40:41]
	s_nop 0
	v_cvt_pk_bf16_f32 v38, v38, v39
	ds_write_b16 v71, v38 offset:4096
	ds_write_b16_d16_hi v71, v38 offset:38912

.LBB0_281:
	s_or_b64 exec, exec, s[0:1]
	v_add_u32_e32 v46, 0x800, v116
	s_waitcnt lgkmcnt(0)
	s_barrier
	ds_read2_b32 v[24:25], v46 offset1:16
	ds_read2_b32 v[26:27], v46 offset0:64 offset1:80
	ds_read2_b32 v[28:29], v46 offset0:128 offset1:144
	ds_read2_b32 v[30:31], v46 offset0:192 offset1:208
	v_add_u32_e32 v47, 0xc00, v116
	s_waitcnt lgkmcnt(3)
	v_mov_b32_e32 v44, v25
	v_mov_b32_e32 v45, v24
	v_pk_add_f32 v[24:25], v[44:45], 0 op_sel_hi:[1,0]
	s_waitcnt lgkmcnt(2)
	v_mov_b32_e32 v44, v27
	v_mov_b32_e32 v45, v26
	ds_read2_b32 v[32:33], v47 offset1:16
	ds_read2_b32 v[34:35], v47 offset0:64 offset1:80
	ds_read2_b32 v[36:37], v47 offset0:128 offset1:144
	ds_read2_b32 v[38:39], v47 offset0:192 offset1:208
	v_pk_add_f32 v[24:25], v[24:25], v[44:45]
	s_waitcnt lgkmcnt(5)
	v_mov_b32_e32 v26, v29
	v_mov_b32_e32 v27, v28
	v_pk_add_f32 v[24:25], v[24:25], v[26:27]
	s_waitcnt lgkmcnt(4)
	v_mov_b32_e32 v26, v31
	v_mov_b32_e32 v27, v30
	v_pk_add_f32 v[24:25], v[24:25], v[26:27]
	s_waitcnt lgkmcnt(3)
	v_mov_b32_e32 v26, v33
	v_mov_b32_e32 v27, v32
	v_pk_add_f32 v[24:25], v[24:25], v[26:27]
	s_waitcnt lgkmcnt(2)
	v_mov_b32_e32 v26, v35
	v_mov_b32_e32 v27, v34
	v_pk_add_f32 v[24:25], v[24:25], v[26:27]
	s_waitcnt lgkmcnt(1)
	v_mov_b32_e32 v26, v37
	v_mov_b32_e32 v27, v36
	v_pk_add_f32 v[24:25], v[24:25], v[26:27]
	s_waitcnt lgkmcnt(0)
	v_mov_b32_e32 v26, v39
	v_mov_b32_e32 v27, v38
	s_mov_b32 s0, 0x358637bd
	v_pk_add_f32 v[24:25], v[24:25], v[26:27]
	v_mov_b64_e32 v[26:27], s[0:1]
	s_brev_b32 s2, 60
	v_pk_fma_f32 v[24:25], v[24:25], s[2:3], v[26:27] op_sel_hi:[1,0,0]
	s_mov_b32 s0, 0x800000
	v_mul_f32_e32 v28, 0x4b800000, v25
	v_cmp_gt_f32_e64 s[44:45], s0, v25
	v_lshlrev_b32_e32 v40, 16, v90
	v_and_b32_e32 v41, 0xffff0000, v90
	v_cndmask_b32_e64 v25, v25, v28, s[44:45]
	v_rsq_f32_e32 v25, v25
	v_lshlrev_b32_e32 v42, 16, v91
	v_and_b32_e32 v43, 0xffff0000, v91
	v_lshl_add_u64 v[22:23], v[92:93], 1, s[80:81]
	v_mul_f32_e32 v30, 0x45800000, v25
	v_cndmask_b32_e64 v30, v25, v30, s[44:45]
	v_mul_f32_e32 v25, 0x4b800000, v24
	v_cmp_gt_f32_e64 s[44:45], s0, v24
	v_pk_mul_f32 v[18:19], v[18:19], v[30:31] op_sel_hi:[1,0]
	v_pk_mul_f32 v[20:21], v[20:21], v[30:31] op_sel_hi:[1,0]
	v_cndmask_b32_e64 v24, v24, v25, s[44:45]
	v_rsq_f32_e32 v24, v24
	v_pk_mul_f32 v[18:19], v[0:1], v[18:19]
	v_pk_mul_f32 v[20:21], v[2:3], v[20:21]
	v_lshlrev_b64 v[28:29], 11, v[88:89]
	v_pk_mul_f32 v[18:19], v[18:19], v[40:41]
	v_pk_mul_f32 v[20:21], v[20:21], v[42:43]
	v_lshl_add_u64 v[28:29], v[22:23], 0, v[28:29]
	v_cvt_pk_bf16_f32 v18, v18, v19
	v_cvt_pk_bf16_f32 v19, v20, v21
	global_store_dwordx2 v[28:29], v[18:19], off
	v_mul_f32_e32 v18, 0x45800000, v24
	v_cndmask_b32_e64 v18, v24, v18, s[44:45]
	v_pk_mul_f32 v[14:15], v[14:15], v[18:19] op_sel_hi:[1,0]
	v_pk_mul_f32 v[16:17], v[16:17], v[18:19] op_sel_hi:[1,0]
	v_pk_mul_f32 v[14:15], v[0:1], v[14:15]
	v_lshlrev_b32_e32 v20, 16, v86
	v_and_b32_e32 v21, 0xffff0000, v86
	v_pk_mul_f32 v[16:17], v[2:3], v[16:17]
	v_lshlrev_b32_e32 v18, 16, v87
	v_and_b32_e32 v19, 0xffff0000, v87
	v_pk_mul_f32 v[14:15], v[14:15], v[20:21]
	v_pk_mul_f32 v[16:17], v[16:17], v[18:19]
	v_cvt_pk_bf16_f32 v14, v14, v15
	v_cvt_pk_bf16_f32 v15, v16, v17
	v_lshlrev_b64 v[16:17], 11, v[84:85]
	v_lshl_add_u64 v[16:17], v[22:23], 0, v[16:17]
	global_store_dwordx2 v[16:17], v[14:15], off
	ds_read2_b32 v[14:15], v46 offset0:32 offset1:48
	ds_read2_b32 v[16:17], v46 offset0:96 offset1:112
	ds_read2_b32 v[18:19], v46 offset0:160 offset1:176
	ds_read2_b32 v[20:21], v46 offset0:224 offset1:240
	ds_read2_b32 v[24:25], v47 offset0:32 offset1:48
	ds_read2_b32 v[28:29], v47 offset0:96 offset1:112
	ds_read2_b32 v[30:31], v47 offset0:160 offset1:176
	ds_read2_b32 v[32:33], v47 offset0:224 offset1:240
	s_waitcnt lgkmcnt(7)
	v_mov_b32_e32 v38, v15
	v_mov_b32_e32 v39, v14
	v_pk_add_f32 v[14:15], v[38:39], 0 op_sel_hi:[1,0]
	s_waitcnt lgkmcnt(6)
	v_mov_b32_e32 v38, v17
	v_mov_b32_e32 v39, v16
	v_pk_add_f32 v[14:15], v[14:15], v[38:39]
	s_waitcnt lgkmcnt(5)
	v_mov_b32_e32 v16, v19
	v_mov_b32_e32 v17, v18
	v_pk_add_f32 v[14:15], v[14:15], v[16:17]
	s_waitcnt lgkmcnt(4)
	v_mov_b32_e32 v16, v21
	v_mov_b32_e32 v17, v20
	v_pk_add_f32 v[14:15], v[14:15], v[16:17]
	s_waitcnt lgkmcnt(3)
	v_mov_b32_e32 v16, v25
	v_mov_b32_e32 v17, v24
	v_pk_add_f32 v[14:15], v[14:15], v[16:17]
	s_waitcnt lgkmcnt(2)
	v_mov_b32_e32 v16, v29
	v_mov_b32_e32 v17, v28
	v_pk_add_f32 v[14:15], v[14:15], v[16:17]
	s_waitcnt lgkmcnt(1)
	v_mov_b32_e32 v16, v31
	v_mov_b32_e32 v17, v30
	v_pk_add_f32 v[14:15], v[14:15], v[16:17]
	s_waitcnt lgkmcnt(0)
	v_mov_b32_e32 v16, v33
	v_mov_b32_e32 v17, v32
	v_pk_add_f32 v[14:15], v[14:15], v[16:17]
	v_lshlrev_b32_e32 v34, 16, v82
	v_pk_fma_f32 v[14:15], v[14:15], s[2:3], v[26:27] op_sel_hi:[1,0,0]
	v_and_b32_e32 v35, 0xffff0000, v82
	v_mul_f32_e32 v16, 0x4b800000, v15
	v_cmp_gt_f32_e64 s[44:45], s0, v15
	v_lshlrev_b32_e32 v36, 16, v83
	v_and_b32_e32 v37, 0xffff0000, v83
	v_cndmask_b32_e64 v15, v15, v16, s[44:45]
	v_rsq_f32_e32 v15, v15
	v_lshlrev_b64 v[16:17], 11, v[80:81]
	v_lshl_add_u64 v[16:17], v[22:23], 0, v[16:17]
	v_mul_f32_e32 v18, 0x45800000, v15
	v_cndmask_b32_e64 v18, v15, v18, s[44:45]
	v_mul_f32_e32 v15, 0x4b800000, v14
	v_cmp_gt_f32_e64 s[44:45], s0, v14
	v_pk_mul_f32 v[10:11], v[10:11], v[18:19] op_sel_hi:[1,0]
	v_pk_mul_f32 v[12:13], v[12:13], v[18:19] op_sel_hi:[1,0]
	v_cndmask_b32_e64 v14, v14, v15, s[44:45]
	v_rsq_f32_e32 v14, v14
	v_pk_mul_f32 v[10:11], v[0:1], v[10:11]
	v_pk_mul_f32 v[12:13], v[2:3], v[12:13]
	v_pk_mul_f32 v[10:11], v[10:11], v[34:35]
	v_pk_mul_f32 v[12:13], v[12:13], v[36:37]
	v_cvt_pk_bf16_f32 v10, v10, v11
	v_cvt_pk_bf16_f32 v11, v12, v13
	global_store_dwordx2 v[16:17], v[10:11], off
	v_mul_f32_e32 v10, 0x45800000, v14
	v_cndmask_b32_e64 v10, v14, v10, s[44:45]
	v_pk_mul_f32 v[6:7], v[6:7], v[10:11] op_sel_hi:[1,0]
	s_nop 0
	v_pk_mul_f32 v[0:1], v[0:1], v[6:7]
	v_lshlrev_b32_e32 v6, 16, v78
	v_and_b32_e32 v7, 0xffff0000, v78
	v_pk_mul_f32 v[0:1], v[0:1], v[6:7]
	v_pk_mul_f32 v[6:7], v[8:9], v[10:11] op_sel_hi:[1,0]
	v_cvt_pk_bf16_f32 v0, v0, v1
	v_pk_mul_f32 v[2:3], v[2:3], v[6:7]
	v_lshlrev_b32_e32 v6, 16, v79
	v_and_b32_e32 v7, 0xffff0000, v79
	v_pk_mul_f32 v[2:3], v[2:3], v[6:7]
	s_nop 0
	v_cvt_pk_bf16_f32 v1, v2, v3
	v_lshlrev_b64 v[2:3], 11, v[76:77]
	v_lshl_add_u64 v[2:3], v[22:23], 0, v[2:3]
	global_store_dwordx2 v[2:3], v[0:1], off
	s_barrier
	s_and_saveexec_b64 s[0:1], vcc
	s_cbranch_execz .LBB0_264
	v_readlane_b32 s2, v254, 42
	s_nop 1
	v_mov_b32_e32 v0, s2
	v_add_u32_e32 v121, s18, v121
	ds_write_b32 v0, v121
	s_branch .LBB0_264

.LBB0_464:
	s_mov_b64 s[22:23], exec
	v_mbcnt_lo_u32_b32 v0, s22, 0
	v_mbcnt_hi_u32_b32 v0, s23, v0
	v_cmp_eq_u32_e32 vcc, 0, v0
	s_and_saveexec_b64 s[14:15], vcc
	s_cbranch_execz .LBB0_466
	s_bcnt1_i32_b64 s2, s[22:23]
	v_mov_b32_e32 v1, s2
	global_atomic_add v167, v5, v1, s[64:65] sc0
.LBB0_466:
	s_or_b64 exec, exec, s[14:15]
	s_or_b64 exec, exec, s[0:1]
	s_cmp_ge_i32 s51, s26
	s_mov_b64 s[0:1], -1
	s_cbranch_scc0 .LBB0_462

.LBB0_817:
	v_readlane_b32 s2, v254, 43
	s_waitcnt vmcnt(0)
	s_nop 0
	v_mov_b32_e32 v0, s2
	v_add_u32_e32 v167, s18, v167
	ds_write_b32 v0, v167
	s_branch .LBB0_459

.LBB0_821:
	s_and_saveexec_b64 s[0:1], vcc
	s_cbranch_execz .LBB0_825
	s_mov_b64 s[22:23], exec
	v_mbcnt_lo_u32_b32 v0, s22, 0
	v_mbcnt_hi_u32_b32 v0, s23, v0
	v_cmp_eq_u32_e64 s[44:45], 0, v0
	s_and_saveexec_b64 s[14:15], s[44:45]
	s_cbranch_execz .LBB0_824
	s_bcnt1_i32_b64 s3, s[22:23]
	v_mov_b32_e32 v1, s3
	global_atomic_add v68, v5, v1, s[46:47] sc0
.LBB0_824:
	s_or_b64 exec, exec, s[14:15]
.LBB0_825:
	s_or_b64 exec, exec, s[0:1]
	s_ashr_i32 s48, s2, 3
	s_abs_i32 s1, s48
	s_and_b32 s22, s2, 7
	s_ashr_i32 s0, s2, 31
	s_mul_hi_u32 s2, s1, s27
	s_mul_i32 s2, s2, s26
	s_sub_i32 s1, s1, s2
	s_sub_i32 s2, s1, s26
	s_cmp_ge_u32 s1, s26
	s_cselect_b32 s1, s2, s1
	s_sub_i32 s2, s1, s26
	s_cmp_ge_u32 s1, s26
	s_cselect_b32 s1, s2, s1
	s_xor_b32 s1, s1, s0
	s_sub_i32 s2, s1, s0
	s_mul_i32 s1, s48, 0xd0000
	v_readlane_b32 s4, v253, 50
	s_mul_hi_i32 s0, s48, 0xd0000
	v_readlane_b32 s5, v253, 51
	s_add_u32 s1, s4, s1
	s_addc_u32 s3, s5, s0
	s_lshl_b32 s0, s22, 8
	s_add_u32 s0, s1, s0
	s_addc_u32 s1, s3, 0
	v_mov_b32_e32 v49, v5
	v_lshl_add_u64 v[14:15], s[0:1], 0, v[48:49]
	v_lshl_add_u64 v[10:11], v[14:15], 0, v[38:39]
	s_movk_i32 s0, 0x1000
	v_add_co_u32_e64 v6, s[44:45], s0, v10
	v_lshl_add_u64 v[22:23], v[14:15], 0, v[40:41]
	s_nop 0
	v_addc_co_u32_e64 v7, s[44:45], 0, v11, s[44:45]
	v_add_co_u32_e64 v18, s[44:45], s0, v22
	global_load_dwordx4 v[0:3], v[6:7], off
	s_nop 0
	global_load_dwordx4 v[6:9], v[6:7], off offset:2048
	s_nop 0
	global_load_dwordx4 v[10:13], v[10:11], off offset:2048
	v_addc_co_u32_e64 v19, s[44:45], 0, v23, s[44:45]
	global_load_dwordx4 v[14:17], v[18:19], off
	s_nop 0
	global_load_dwordx4 v[18:21], v[18:19], off offset:2048
	s_nop 0
	global_load_dwordx4 v[22:25], v[22:23], off offset:2048
	s_cmp_eq_u32 s2, 0
	s_cselect_b64 s[0:1], -1, 0
	v_or_b32_e32 v27, s2, v57
	v_cmp_eq_u32_e64 s[44:45], 0, v27
	v_readfirstlane_b32 s2, v47
	s_waitcnt vmcnt(0)
	ds_write_b128 v51, v[0:3] offset:59392
	ds_write_b128 v52, v[6:9] offset:17408
	ds_write_b16 v53, v10 offset:40960
	ds_write_b16_d16_hi v53, v10 offset:41104
	ds_write_b16 v53, v11 offset:41248
	ds_write_b16_d16_hi v53, v11 offset:41392
	ds_write_b16 v53, v12 offset:41536
	ds_write_b16_d16_hi v53, v12 offset:41680
	ds_write_b16 v53, v13 offset:41824
	ds_write_b16_d16_hi v53, v13 offset:41968
	ds_write_b128 v54, v[14:17] offset:59392
	ds_write_b128 v55, v[18:21] offset:17408
	ds_write_b16 v56, v22 offset:40960
	ds_write_b16_d16_hi v56, v22 offset:41104
	ds_write_b16 v56, v23 offset:41248
	ds_write_b16_d16_hi v56, v23 offset:41392
	ds_write_b16 v56, v24 offset:41536
	ds_write_b16_d16_hi v56, v24 offset:41680
	ds_write_b16 v56, v25 offset:41824
	ds_write_b16_d16_hi v56, v25 offset:41968
	s_waitcnt lgkmcnt(0)
	s_barrier
	ds_read_u16 v0, v58 offset:59392
	ds_read_u16 v1, v58 offset:59664
	ds_read_u16 v2, v58 offset:59936
	ds_read_u16 v3, v58 offset:60208
	ds_read_u16 v6, v58 offset:60480
	ds_read_u16 v7, v58 offset:60752
	ds_read_u16 v8, v58 offset:61024
	ds_read_u16 v9, v58 offset:61296
	ds_read_u16 v10, v58 offset:61568
	ds_read_u16 v11, v58 offset:61840
	ds_read_u16 v12, v58 offset:62112
	ds_read_u16 v13, v58 offset:62384
	ds_read_u16 v14, v58 offset:62656
	ds_read_u16 v15, v58 offset:62928
	ds_read_u16 v16, v58 offset:63200
	ds_read_u16 v17, v58 offset:63472
	s_waitcnt lgkmcnt(14)
	v_lshlrev_b32_e32 v0, 16, v0
	v_lshlrev_b32_e32 v1, 16, v1
	v_cndmask_b32_e64 v18, v0, 0, s[0:1]
	s_waitcnt lgkmcnt(13)
	v_lshlrev_b32_e32 v2, 16, v2
	v_cndmask_b32_e64 v19, v1, 0, s[0:1]
	v_add_f32_e32 v0, 0, v18
	s_waitcnt lgkmcnt(12)
	v_lshlrev_b32_e32 v3, 16, v3
	v_cndmask_b32_e64 v2, v2, 0, s[0:1]
	v_add_f32_e32 v0, v0, v19
	s_waitcnt lgkmcnt(11)
	v_lshlrev_b32_e32 v6, 16, v6
	v_cndmask_b32_e64 v3, v3, 0, s[0:1]
	v_add_f32_e32 v0, v0, v2
	s_waitcnt lgkmcnt(10)
	v_lshlrev_b32_e32 v7, 16, v7
	v_cndmask_b32_e64 v6, v6, 0, s[0:1]
	v_add_f32_e32 v0, v0, v3
	s_waitcnt lgkmcnt(9)
	v_lshlrev_b32_e32 v8, 16, v8
	v_cndmask_b32_e64 v7, v7, 0, s[0:1]
	v_add_f32_e32 v0, v0, v6
	s_waitcnt lgkmcnt(8)
	v_lshlrev_b32_e32 v9, 16, v9
	v_cndmask_b32_e64 v8, v8, 0, s[0:1]
	v_add_f32_e32 v0, v0, v7
	s_waitcnt lgkmcnt(7)
	v_lshlrev_b32_e32 v10, 16, v10
	v_cndmask_b32_e64 v9, v9, 0, s[0:1]
	v_add_f32_e32 v0, v0, v8
	s_waitcnt lgkmcnt(6)
	v_lshlrev_b32_e32 v11, 16, v11
	v_cndmask_b32_e64 v10, v10, 0, s[0:1]
	v_add_f32_e32 v0, v0, v9
	s_waitcnt lgkmcnt(5)
	v_lshlrev_b32_e32 v12, 16, v12
	v_cndmask_b32_e64 v11, v11, 0, s[0:1]
	v_add_f32_e32 v0, v0, v10
	s_waitcnt lgkmcnt(4)
	v_lshlrev_b32_e32 v13, 16, v13
	v_cndmask_b32_e64 v12, v12, 0, s[0:1]
	v_add_f32_e32 v0, v0, v11
	s_waitcnt lgkmcnt(2)
	v_lshlrev_b32_e32 v1, 16, v15
	v_lshlrev_b32_e32 v14, 16, v14
	v_cndmask_b32_e64 v13, v13, 0, s[0:1]
	v_add_f32_e32 v0, v0, v12
	v_cndmask_b32_e64 v15, v1, 0, s[0:1]
	s_waitcnt lgkmcnt(1)
	v_lshlrev_b32_e32 v1, 16, v16
	v_cndmask_b32_e64 v14, v14, 0, s[0:1]
	v_add_f32_e32 v0, v0, v13
	v_cndmask_b32_e64 v16, v1, 0, s[0:1]
	s_waitcnt lgkmcnt(0)
	v_lshlrev_b32_e32 v1, 16, v17
	v_add_f32_e32 v0, v0, v14
	v_cndmask_b32_e64 v17, v1, 0, s[0:1]
	ds_read_u16 v1, v58 offset:63744
	ds_read_u16 v20, v58 offset:64016
	ds_read_u16 v21, v58 offset:64288
	ds_read_u16 v22, v58 offset:64560
	ds_read_u16 v23, v58 offset:64832
	ds_read_u16 v24, v58 offset:65104
	ds_read_u16 v25, v58 offset:65376
	ds_read_u16 v26, v59 offset:6256
	v_add_f32_e32 v0, v0, v15
	s_waitcnt lgkmcnt(7)
	v_lshlrev_b32_e32 v1, 16, v1
	v_add_f32_e32 v0, v0, v16
	v_cndmask_b32_e64 v27, v1, 0, s[44:45]
	s_waitcnt lgkmcnt(6)
	v_lshlrev_b32_e32 v1, 16, v20
	v_add_f32_e32 v0, v0, v17
	v_cndmask_b32_e64 v20, v1, 0, s[44:45]
	s_waitcnt lgkmcnt(5)
	v_lshlrev_b32_e32 v1, 16, v21
	v_add_f32_e32 v0, v0, v27
	v_cndmask_b32_e64 v21, v1, 0, s[44:45]
	s_waitcnt lgkmcnt(4)
	v_lshlrev_b32_e32 v1, 16, v22
	v_add_f32_e32 v0, v0, v20
	v_cndmask_b32_e64 v22, v1, 0, s[44:45]
	s_waitcnt lgkmcnt(3)
	v_lshlrev_b32_e32 v1, 16, v23
	v_add_f32_e32 v0, v0, v21
	v_cndmask_b32_e64 v23, v1, 0, s[44:45]
	s_waitcnt lgkmcnt(2)
	v_lshlrev_b32_e32 v1, 16, v24
	v_add_f32_e32 v0, v0, v22
	v_cndmask_b32_e64 v24, v1, 0, s[44:45]
	s_waitcnt lgkmcnt(1)
	v_lshlrev_b32_e32 v1, 16, v25
	v_add_f32_e32 v0, v0, v23
	v_cndmask_b32_e64 v25, v1, 0, s[44:45]
	s_waitcnt lgkmcnt(0)
	v_lshlrev_b32_e32 v1, 16, v26
	v_add_f32_e32 v0, v0, v24
	v_cndmask_b32_e64 v26, v1, 0, s[44:45]
	ds_read_u16 v1, v59 offset:6528
	ds_read_u16 v28, v59 offset:6800
	ds_read_u16 v29, v59 offset:7072
	ds_read_u16 v30, v59 offset:7344
	ds_read_u16 v31, v59 offset:7616
	ds_read_u16 v32, v59 offset:7888
	ds_read_u16 v33, v59 offset:8160
	ds_read_u16 v34, v59 offset:8432
	v_add_f32_e32 v0, v0, v25
	s_waitcnt lgkmcnt(7)
	v_lshlrev_b32_e32 v1, 16, v1
	v_add_f32_e32 v0, v0, v26
	v_cndmask_b32_e64 v35, v1, 0, s[44:45]
	s_waitcnt lgkmcnt(6)
	v_lshlrev_b32_e32 v1, 16, v28
	v_add_f32_e32 v0, v0, v35
	v_cndmask_b32_e64 v28, v1, 0, s[44:45]
	s_waitcnt lgkmcnt(5)
	v_lshlrev_b32_e32 v1, 16, v29
	v_add_f32_e32 v0, v0, v28
	v_cndmask_b32_e64 v29, v1, 0, s[44:45]
	s_waitcnt lgkmcnt(4)
	v_lshlrev_b32_e32 v1, 16, v30
	v_add_f32_e32 v0, v0, v29
	v_cndmask_b32_e64 v30, v1, 0, s[44:45]
	s_waitcnt lgkmcnt(3)
	v_lshlrev_b32_e32 v1, 16, v31
	v_add_f32_e32 v0, v0, v30
	v_cndmask_b32_e64 v31, v1, 0, s[44:45]
	s_waitcnt lgkmcnt(2)
	v_lshlrev_b32_e32 v1, 16, v32
	v_add_f32_e32 v0, v0, v31
	v_cndmask_b32_e64 v32, v1, 0, s[44:45]
	s_waitcnt lgkmcnt(1)
	v_lshlrev_b32_e32 v1, 16, v33
	v_add_f32_e32 v0, v0, v32
	v_cndmask_b32_e64 v33, v1, 0, s[44:45]
	s_waitcnt lgkmcnt(0)
	v_lshlrev_b32_e32 v1, 16, v34
	v_add_f32_e32 v0, v0, v33
	v_cndmask_b32_e64 v34, v1, 0, s[44:45]
	v_add_f32_e32 v0, v0, v34
	ds_write_b32 v60, v0
	s_waitcnt lgkmcnt(0)
	s_barrier
	ds_read_b32 v1, v61
	v_mul_f32_e32 v18, 0x3fb8aa3b, v18
	v_mul_f32_e32 v19, 0x3fb8aa3b, v19
	v_mul_f32_e32 v36, 0x3fb8aa3b, v2
	v_mul_f32_e32 v37, 0x3fb8aa3b, v3
	v_mul_f32_e32 v6, 0x3fb8aa3b, v6
	v_mul_f32_e32 v7, 0x3fb8aa3b, v7
	v_mul_f32_e32 v8, 0x3fb8aa3b, v8
	v_mul_f32_e32 v9, 0x3fb8aa3b, v9
	v_mul_f32_e32 v10, 0x3fb8aa3b, v10
	v_mul_f32_e32 v11, 0x3fb8aa3b, v11
	v_mul_f32_e32 v12, 0x3fb8aa3b, v12
	v_mul_f32_e32 v13, 0x3fb8aa3b, v13
	v_mul_f32_e32 v14, 0x3fb8aa3b, v14
	v_mul_f32_e32 v15, 0x3fb8aa3b, v15
	v_mul_f32_e32 v16, 0x3fb8aa3b, v16
	v_mul_f32_e32 v17, 0x3fb8aa3b, v17
	v_mul_f32_e32 v27, 0x3fb8aa3b, v27
	v_mul_f32_e32 v20, 0x3fb8aa3b, v20
	v_mul_f32_e32 v21, 0x3fb8aa3b, v21
	v_mul_f32_e32 v22, 0x3fb8aa3b, v22
	v_mul_f32_e32 v23, 0x3fb8aa3b, v23
	v_mul_f32_e32 v24, 0x3fb8aa3b, v24
	v_mul_f32_e32 v25, 0x3fb8aa3b, v25
	v_mul_f32_e32 v26, 0x3fb8aa3b, v26
	v_mul_f32_e32 v35, 0x3fb8aa3b, v35
	v_mul_f32_e32 v28, 0x3fb8aa3b, v28
	v_mul_f32_e32 v29, 0x3fb8aa3b, v29
	v_mul_f32_e32 v30, 0x3fb8aa3b, v30
	v_mul_f32_e32 v31, 0x3fb8aa3b, v31
	v_mul_f32_e32 v32, 0x3fb8aa3b, v32
	v_mul_f32_e32 v33, 0x3fb8aa3b, v33
	v_mul_f32_e32 v34, 0x3fb8aa3b, v34
	v_exp_f32_e32 v80, v18
	v_exp_f32_e32 v2, v19
	v_exp_f32_e32 v3, v36
	v_exp_f32_e32 v69, v37
	v_exp_f32_e32 v49, v6
	v_exp_f32_e32 v70, v7
	v_exp_f32_e32 v71, v8
	v_exp_f32_e32 v72, v9
	v_exp_f32_e32 v73, v10
	v_exp_f32_e32 v74, v11
	v_exp_f32_e32 v75, v12
	v_exp_f32_e32 v76, v13
	v_exp_f32_e32 v77, v14
	v_exp_f32_e32 v78, v15
	v_exp_f32_e32 v79, v16
	v_exp_f32_e32 v81, v17
	v_exp_f32_e32 v82, v27
	v_exp_f32_e32 v83, v20
	v_exp_f32_e32 v84, v21
	v_exp_f32_e32 v85, v22
	v_exp_f32_e32 v86, v23
	v_exp_f32_e32 v87, v24
	v_exp_f32_e32 v88, v25
	v_exp_f32_e32 v89, v26
	v_exp_f32_e32 v90, v35
	v_exp_f32_e32 v91, v28
	v_exp_f32_e32 v92, v29
	v_exp_f32_e32 v93, v30
	v_exp_f32_e32 v94, v31
	v_exp_f32_e32 v96, v32
	v_exp_f32_e32 v95, v33
	v_exp_f32_e32 v97, v34
	s_waitcnt lgkmcnt(0)
	v_mul_f32_e32 v98, 0x3fb8aa3b, v1
	s_and_saveexec_b64 s[0:1], s[38:39]
	s_xor_b64 s[0:1], exec, s[0:1]
	s_cbranch_execz .LBB0_827
	v_cndmask_b32_e64 v6, v98, 0, s[40:41]
	v_exp_f32_e32 v6, v6
	v_sub_f32_e32 v35, 1.0, v96
	v_sub_f32_e32 v37, 1.0, v97
	v_sub_f32_e32 v36, 1.0, v95
	v_mul_f32_e32 v7, v80, v6
	v_mul_f32_e32 v8, v2, v7
	v_mul_f32_e32 v9, v3, v8
	v_mul_f32_e32 v10, v69, v9
	v_mul_f32_e32 v11, v49, v10
	v_mul_f32_e32 v12, v70, v11
	v_mul_f32_e32 v13, v71, v12
	v_mul_f32_e32 v14, v72, v13
	v_mul_f32_e32 v15, v73, v14
	v_mul_f32_e32 v16, v74, v15
	v_mul_f32_e32 v17, v75, v16
	v_mul_f32_e32 v18, v76, v17
	v_mul_f32_e32 v19, v77, v18
	v_mul_f32_e32 v20, v78, v19
	v_mul_f32_e32 v21, v79, v20
	v_mul_f32_e32 v22, v81, v21
	v_mul_f32_e32 v23, v82, v22
	v_mul_f32_e32 v24, v83, v23
	v_mul_f32_e32 v25, v84, v24
	v_mul_f32_e32 v26, v85, v25
	v_mul_f32_e32 v27, v86, v26
	v_mul_f32_e32 v28, v87, v27
	v_mul_f32_e32 v29, v88, v28
	v_mul_f32_e32 v30, v89, v29
	v_mul_f32_e32 v31, v90, v30
	v_mul_f32_e32 v32, v91, v31
	v_mul_f32_e32 v33, v92, v32
	v_mul_f32_e32 v98, v93, v33
	v_mul_f32_e32 v99, v94, v98
	v_mul_f32_e32 v96, v96, v99
	v_mul_f32_e32 v97, v95, v96
	v_sub_f32_e32 v34, 1.0, v94
	v_sub_f32_e32 v93, 1.0, v93
	v_sub_f32_e32 v92, 1.0, v92
	v_sub_f32_e32 v91, 1.0, v91
	v_sub_f32_e32 v90, 1.0, v90
	v_sub_f32_e32 v89, 1.0, v89
	v_sub_f32_e32 v88, 1.0, v88
	v_sub_f32_e32 v87, 1.0, v87
	v_sub_f32_e32 v86, 1.0, v86
	v_sub_f32_e32 v85, 1.0, v85
	v_sub_f32_e32 v84, 1.0, v84
	v_sub_f32_e32 v83, 1.0, v83
	v_sub_f32_e32 v82, 1.0, v82
	v_sub_f32_e32 v95, 1.0, v81
	v_sub_f32_e32 v94, 1.0, v79
	v_sub_f32_e32 v79, 1.0, v78
	v_sub_f32_e32 v78, 1.0, v77
	v_sub_f32_e32 v77, 1.0, v76
	v_sub_f32_e32 v76, 1.0, v75
	v_sub_f32_e32 v75, 1.0, v74
	v_sub_f32_e32 v74, 1.0, v73
	v_sub_f32_e32 v73, 1.0, v72
	v_sub_f32_e32 v72, 1.0, v71
	v_sub_f32_e32 v71, 1.0, v70
	v_sub_f32_e32 v70, 1.0, v49
	v_sub_f32_e32 v101, 1.0, v69
	v_sub_f32_e32 v100, 1.0, v3
	v_sub_f32_e32 v3, 1.0, v2
	v_sub_f32_e32 v2, 1.0, v80
	v_pk_mul_f32 v[6:7], v[2:3], v[6:7]
	v_pk_mul_f32 v[8:9], v[100:101], v[8:9]
	v_pk_mul_f32 v[10:11], v[70:71], v[10:11]
	v_pk_mul_f32 v[12:13], v[72:73], v[12:13]
	v_pk_mul_f32 v[14:15], v[74:75], v[14:15]
	v_pk_mul_f32 v[16:17], v[76:77], v[16:17]
	v_pk_mul_f32 v[18:19], v[78:79], v[18:19]
	v_pk_mul_f32 v[20:21], v[94:95], v[20:21]
	v_pk_mul_f32 v[22:23], v[82:83], v[22:23]
	v_pk_mul_f32 v[24:25], v[84:85], v[24:25]
	v_pk_mul_f32 v[26:27], v[86:87], v[26:27]
	v_pk_mul_f32 v[28:29], v[88:89], v[28:29]
	v_pk_mul_f32 v[30:31], v[90:91], v[30:31]
	v_pk_mul_f32 v[32:33], v[92:93], v[32:33]
	v_pk_mul_f32 v[34:35], v[34:35], v[98:99]
	v_pk_mul_f32 v[36:37], v[36:37], v[96:97]

.LBB0_833:
	s_or_b64 exec, exec, s[0:1]
	s_ashr_i32 s0, s2, 8
	s_and_b32 s3, s2, 64
	s_lshl_b32 s1, s0, 7
	s_or_b32 s1, s1, s3
	v_or_b32_e32 v0, s1, v50
	s_movk_i32 s1, 0x90
	s_bfe_u32 s2, s2, 0x10007
	v_mad_u64_u32 v[36:37], s[4:5], v0, s1, v[46:47]
	s_waitcnt lgkmcnt(0)
	s_barrier
	v_lshl_or_b32 v6, s2, 6, v50
	ds_read_b128 v[0:3], v36 offset:4096
	v_mad_u32_u24 v37, v6, s1, 0
	v_or_b32_e32 v49, 16, v50
	v_or_b32_e32 v114, 32, v50
	v_or_b32_e32 v118, 48, v50
	v_add_u32_e32 v69, 0x900, v37
	v_bitop3_b32 v7, v49, v63, 24 bitop3:0x6c
	v_add_u32_e32 v115, 0x1200, v37
	v_bitop3_b32 v20, v114, v63, 40 bitop3:0x6c
	v_add_u32_e32 v119, 0x1b00, v37
	v_bitop3_b32 v28, v118, v63, 56 bitop3:0x6c
	v_lshl_add_u32 v6, v64, 1, v37
	v_lshl_add_u32 v10, v7, 1, v69
	v_lshl_add_u32 v20, v20, 1, v115
	v_lshl_add_u32 v32, v28, 1, v119
	ds_read_b128 v[6:9], v6 offset:40960
	ds_read_b128 v[10:13], v10 offset:40960
	ds_read_b128 v[20:23], v20 offset:40960
	ds_read_b128 v[32:35], v32 offset:40960
	s_waitcnt lgkmcnt(3)
	v_mfma_f32_16x16x32_bf16 v[16:19], v[0:3], v[6:9], 0
	ds_read_b128 v[106:109], v36 offset:11008
	v_lshl_add_u32 v37, v66, 1, v37
	s_ashr_i32 s1, s0, 31
	s_waitcnt lgkmcnt(3)
	v_mfma_f32_16x16x32_bf16 v[24:27], v[0:3], v[10:13], 0
	v_lshl_add_u64 v[14:15], v[14:15], 0, s[0:1]
	v_readlane_b32 s0, v254, 1
	v_lshlrev_b64 v[14:15], 15, v[14:15]
	s_waitcnt lgkmcnt(2)
	v_mfma_f32_16x16x32_bf16 v[28:31], v[0:3], v[20:23], 0
	v_readlane_b32 s1, v254, 2
	s_waitcnt lgkmcnt(1)
	v_mfma_f32_16x16x32_bf16 v[70:73], v[0:3], v[32:35], 0
	ds_read_b128 v[0:3], v36 offset:6400
	v_lshl_add_u64 v[14:15], s[0:1], 0, v[14:15]
	s_waitcnt lgkmcnt(0)
	v_mfma_f32_16x16x32_bf16 v[74:77], v[0:3], v[6:9], 0
	v_mfma_f32_16x16x32_bf16 v[78:81], v[0:3], v[10:13], 0
	v_mfma_f32_16x16x32_bf16 v[82:85], v[0:3], v[20:23], 0
	v_mfma_f32_16x16x32_bf16 v[86:89], v[0:3], v[32:35], 0
	ds_read_b128 v[0:3], v36 offset:8704
	s_waitcnt lgkmcnt(0)
	v_mfma_f32_16x16x32_bf16 v[90:93], v[0:3], v[6:9], 0
	v_mfma_f32_16x16x32_bf16 v[94:97], v[0:3], v[10:13], 0
	v_mfma_f32_16x16x32_bf16 v[98:101], v[0:3], v[20:23], 0
	v_mfma_f32_16x16x32_bf16 v[102:105], v[0:3], v[32:35], 0
	v_mfma_f32_16x16x32_bf16 v[0:3], v[106:109], v[6:9], 0
	v_mfma_f32_16x16x32_bf16 v[6:9], v[106:109], v[10:13], 0
	v_mfma_f32_16x16x32_bf16 v[10:13], v[106:109], v[20:23], 0
	ds_read_b128 v[20:23], v36 offset:4160
	v_mfma_f32_16x16x32_bf16 v[32:35], v[106:109], v[32:35], 0
	ds_read_b128 v[106:109], v37 offset:40960
	v_bitop3_b32 v37, v49, v65, 24 bitop3:0x6c
	v_lshl_add_u32 v37, v37, 1, v69
	ds_read_b128 v[110:113], v37 offset:40960
	v_bitop3_b32 v37, v114, v65, 40 bitop3:0x6c
	v_lshl_add_u32 v37, v37, 1, v115
	ds_read_b128 v[114:117], v37 offset:40960
	v_bitop3_b32 v37, v118, v65, 56 bitop3:0x6c
	v_lshl_add_u32 v37, v37, 1, v119
	ds_read_b128 v[118:121], v37 offset:40960
	s_waitcnt lgkmcnt(3)
	v_mfma_f32_16x16x32_bf16 v[16:19], v[20:23], v[106:109], v[16:19]
	s_waitcnt lgkmcnt(2)
	v_mfma_f32_16x16x32_bf16 v[24:27], v[20:23], v[110:113], v[24:27]
	s_waitcnt lgkmcnt(1)
	v_mfma_f32_16x16x32_bf16 v[28:31], v[20:23], v[114:117], v[28:31]
	s_waitcnt lgkmcnt(0)
	v_mfma_f32_16x16x32_bf16 v[20:23], v[20:23], v[118:121], v[70:73]
	s_nop 2
	ds_read_b128 v[70:73], v36 offset:6464
	s_waitcnt lgkmcnt(0)
	v_mfma_f32_16x16x32_bf16 v[74:77], v[70:73], v[106:109], v[74:77]
	v_mfma_f32_16x16x32_bf16 v[78:81], v[70:73], v[110:113], v[78:81]
	v_mfma_f32_16x16x32_bf16 v[82:85], v[70:73], v[114:117], v[82:85]
	v_mfma_f32_16x16x32_bf16 v[70:73], v[70:73], v[118:121], v[86:89]
	s_nop 2
	ds_read_b128 v[86:89], v36 offset:8768
	s_waitcnt lgkmcnt(0)
	v_mfma_f32_16x16x32_bf16 v[90:93], v[86:89], v[106:109], v[90:93]
	v_mfma_f32_16x16x32_bf16 v[94:97], v[86:89], v[110:113], v[94:97]
	v_mfma_f32_16x16x32_bf16 v[98:101], v[86:89], v[114:117], v[98:101]
	v_mfma_f32_16x16x32_bf16 v[86:89], v[86:89], v[118:121], v[102:105]
	s_nop 2
	ds_read_b128 v[102:105], v36 offset:11072
	s_waitcnt lgkmcnt(0)
	v_mfma_f32_16x16x32_bf16 v[0:3], v[102:105], v[106:109], v[0:3]
	v_mfma_f32_16x16x32_bf16 v[6:9], v[102:105], v[110:113], v[6:9]
	v_mfma_f32_16x16x32_bf16 v[10:13], v[102:105], v[114:117], v[10:13]
	v_mfma_f32_16x16x32_bf16 v[32:35], v[102:105], v[118:121], v[32:35]
	s_lshl_b32 s96, s3, 1
	v_lshl_add_u64 v[14:15], v[14:15], 0, s[96:97]
	v_lshl_add_u64 v[14:15], v[14:15], 0, v[4:5]
	v_cvt_pk_bf16_f32 v16, v16, v17
	v_cvt_pk_bf16_f32 v17, v18, v19
	v_lshl_or_b32 v18, s2, 14, v67
	v_mov_b32_e32 v19, v5
	v_lshl_add_u64 v[36:37], v[14:15], 0, v[18:19]
	global_store_dwordx2 v[36:37], v[16:17], off
	v_cvt_pk_bf16_f32 v16, v24, v25
	v_or_b32_e32 v24, 0x1000, v18
	v_mov_b32_e32 v25, v5
	v_cvt_pk_bf16_f32 v17, v26, v27
	v_lshl_add_u64 v[26:27], v[14:15], 0, v[24:25]
	global_store_dwordx2 v[26:27], v[16:17], off
	v_or_b32_e32 v26, 0x2000, v18
	v_mov_b32_e32 v27, v5
	v_cvt_pk_bf16_f32 v16, v28, v29
	v_cvt_pk_bf16_f32 v17, v30, v31
	v_lshl_add_u64 v[28:29], v[14:15], 0, v[26:27]
	v_or_b32_e32 v18, 0x3000, v18
	global_store_dwordx2 v[28:29], v[16:17], off
	v_cvt_pk_bf16_f32 v16, v20, v21
	v_cvt_pk_bf16_f32 v17, v22, v23
	v_lshl_add_u64 v[20:21], v[14:15], 0, v[18:19]
	global_store_dwordx2 v[20:21], v[16:17], off
	v_lshl_add_u64 v[16:17], v[14:15], 0, 32
	v_cvt_pk_bf16_f32 v20, v74, v75
	v_cvt_pk_bf16_f32 v21, v76, v77
	global_store_dwordx2 v[36:37], v[20:21], off offset:32
	v_cvt_pk_bf16_f32 v20, v78, v79
	v_cvt_pk_bf16_f32 v21, v80, v81
	v_lshl_add_u64 v[22:23], v[16:17], 0, v[24:25]
	global_store_dwordx2 v[22:23], v[20:21], off
	v_cvt_pk_bf16_f32 v20, v82, v83
	v_cvt_pk_bf16_f32 v21, v84, v85
	v_lshl_add_u64 v[22:23], v[16:17], 0, v[26:27]
	global_store_dwordx2 v[22:23], v[20:21], off
	v_cvt_pk_bf16_f32 v20, v70, v71
	v_cvt_pk_bf16_f32 v21, v72, v73
	v_lshl_add_u64 v[16:17], v[16:17], 0, v[18:19]
	s_mov_b64 s[0:1], 0x60
	global_store_dwordx2 v[16:17], v[20:21], off
	v_lshl_add_u64 v[16:17], v[14:15], 0, 64
	v_cvt_pk_bf16_f32 v20, v90, v91
	v_cvt_pk_bf16_f32 v21, v92, v93
	v_lshl_add_u64 v[14:15], v[14:15], 0, s[0:1]
	v_cvt_pk_bf16_f32 v0, v0, v1
	v_cvt_pk_bf16_f32 v1, v2, v3
	global_store_dwordx2 v[36:37], v[20:21], off offset:64
	v_cvt_pk_bf16_f32 v20, v94, v95
	v_cvt_pk_bf16_f32 v21, v96, v97
	v_lshl_add_u64 v[22:23], v[16:17], 0, v[24:25]
	global_store_dwordx2 v[36:37], v[0:1], off offset:96
	v_cvt_pk_bf16_f32 v0, v6, v7
	v_cvt_pk_bf16_f32 v1, v8, v9
	v_lshl_add_u64 v[2:3], v[14:15], 0, v[24:25]
	global_store_dwordx2 v[22:23], v[20:21], off
	v_cvt_pk_bf16_f32 v20, v98, v99
	v_cvt_pk_bf16_f32 v21, v100, v101
	v_lshl_add_u64 v[22:23], v[16:17], 0, v[26:27]
	global_store_dwordx2 v[2:3], v[0:1], off
	v_cvt_pk_bf16_f32 v0, v10, v11
	v_cvt_pk_bf16_f32 v1, v12, v13
	v_lshl_add_u64 v[2:3], v[14:15], 0, v[26:27]
	global_store_dwordx2 v[22:23], v[20:21], off
	v_cvt_pk_bf16_f32 v20, v86, v87
	v_cvt_pk_bf16_f32 v21, v88, v89
	v_lshl_add_u64 v[16:17], v[16:17], 0, v[18:19]
	global_store_dwordx2 v[2:3], v[0:1], off
	v_cvt_pk_bf16_f32 v0, v32, v33
	v_cvt_pk_bf16_f32 v1, v34, v35
	v_lshl_add_u64 v[2:3], v[14:15], 0, v[18:19]
	global_store_dwordx2 v[16:17], v[20:21], off
	global_store_dwordx2 v[2:3], v[0:1], off
	s_barrier
	s_and_saveexec_b64 s[0:1], vcc
	s_cbranch_execz .LBB0_820
	v_readlane_b32 s2, v254, 44
	s_nop 1
	v_mov_b32_e32 v0, s2
	v_add_u32_e32 v68, s18, v68
	ds_write_b32 v0, v68
	s_branch .LBB0_820
